# fused epilogue mode 0: X tile stored right after the row statistics are published (overlaps the exchange wait); last loop writes only XN
# baseline (speedup 1.0000x reference)
.LBB0_580:
	s_cmp_lg_u32 s61, 0
	s_cbranch_scc1 .Lmy_xs1_skip
	v_lshl_add_u64 v[166:167], s[24:25], 0, v[208:209]
	v_lshl_add_u64 v[166:167], v[184:185], 2, v[166:167]
	global_store_dwordx4 v[166:167], v[134:137], off
	global_store_dwordx4 v[166:167], v[130:133], off offset:64
	global_store_dwordx4 v[166:167], v[126:129], off offset:512
	global_store_dwordx4 v[166:167], v[122:125], off offset:576
	v_lshl_add_u64 v[168:169], s[24:25], 0, v[204:205]
	v_lshl_add_u64 v[168:169], v[184:185], 2, v[168:169]
	global_store_dwordx4 v[168:169], v[118:121], off
	global_store_dwordx4 v[168:169], v[114:117], off offset:64
	global_store_dwordx4 v[168:169], v[110:113], off offset:512
	global_store_dwordx4 v[168:169], v[106:109], off offset:576
	v_lshl_add_u64 v[166:167], s[24:25], 0, v[206:207]
	v_lshl_add_u64 v[166:167], v[184:185], 2, v[166:167]
	global_store_dwordx4 v[166:167], v[102:105], off
	global_store_dwordx4 v[166:167], v[98:101], off offset:64
	global_store_dwordx4 v[166:167], v[94:97], off offset:512
	global_store_dwordx4 v[166:167], v[90:93], off offset:576
	v_lshl_add_u64 v[168:169], s[24:25], 0, v[198:199]
	v_lshl_add_u64 v[168:169], v[184:185], 2, v[168:169]
	global_store_dwordx4 v[168:169], v[86:89], off
	global_store_dwordx4 v[168:169], v[82:85], off offset:64
	global_store_dwordx4 v[168:169], v[78:81], off offset:512
	global_store_dwordx4 v[168:169], v[74:77], off offset:576
	v_lshl_add_u64 v[166:167], s[24:25], 0, v[196:197]
	v_lshl_add_u64 v[166:167], v[184:185], 2, v[166:167]
	global_store_dwordx4 v[166:167], v[70:73], off
	global_store_dwordx4 v[166:167], v[66:69], off offset:64
	global_store_dwordx4 v[166:167], v[62:65], off offset:512
	global_store_dwordx4 v[166:167], v[58:61], off offset:576
	v_lshl_add_u64 v[168:169], s[24:25], 0, v[190:191]
	v_lshl_add_u64 v[168:169], v[184:185], 2, v[168:169]
	global_store_dwordx4 v[168:169], v[54:57], off
	global_store_dwordx4 v[168:169], v[50:53], off offset:64
	global_store_dwordx4 v[168:169], v[42:45], off offset:512
	global_store_dwordx4 v[168:169], v[38:41], off offset:576
	v_lshl_add_u64 v[166:167], s[24:25], 0, v[188:189]
	v_lshl_add_u64 v[166:167], v[184:185], 2, v[166:167]
	global_store_dwordx4 v[166:167], v[28:31], off
	global_store_dwordx4 v[166:167], v[24:27], off offset:64
	global_store_dwordx4 v[166:167], v[20:23], off offset:512
	global_store_dwordx4 v[166:167], v[16:19], off offset:576
	v_lshl_add_u64 v[168:169], s[24:25], 0, v[174:175]
	v_lshl_add_u64 v[168:169], v[184:185], 2, v[168:169]
	global_store_dwordx4 v[168:169], v[12:15], off
	global_store_dwordx4 v[168:169], v[8:11], off offset:64
	global_store_dwordx4 v[168:169], v[4:7], off offset:512
	global_store_dwordx4 v[168:169], v[0:3], off offset:576

.LBB0_598:
	v_lshlrev_b64 v[34:35], 11, v[34:35]
	v_lshl_add_u64 v[34:35], s[26:27], 0, v[34:35]
	s_andn2_b64 vcc, exec, s[34:35]
	v_lshl_add_u64 v[34:35], v[184:185], 1, v[34:35]
	s_cbranch_vccnz .LBB0_600
	s_nop 1
	v_cvt_pk_bf16_f32 v134, v166, v167
	v_cvt_pk_bf16_f32 v135, v168, v169
	flat_store_dwordx2 v[34:35], v[134:135]

.LBB0_602:
	s_andn2_b64 vcc, exec, s[34:35]
	s_cbranch_vccnz .LBB0_604
	s_nop 1
	v_cvt_pk_bf16_f32 v130, v134, v135
	v_cvt_pk_bf16_f32 v131, v136, v137
	flat_store_dwordx2 v[34:35], v[130:131] offset:32

.LBB0_606:
	s_andn2_b64 vcc, exec, s[34:35]
	s_cbranch_vccnz .LBB0_608
	s_nop 1
	v_cvt_pk_bf16_f32 v126, v130, v131
	v_cvt_pk_bf16_f32 v127, v132, v133
	flat_store_dwordx2 v[34:35], v[126:127] offset:256

.LBB0_610:
	s_andn2_b64 vcc, exec, s[34:35]
	s_cbranch_vccnz .LBB0_612
	s_nop 1
	v_cvt_pk_bf16_f32 v122, v126, v127
	v_cvt_pk_bf16_f32 v123, v128, v129
	flat_store_dwordx2 v[34:35], v[122:123] offset:288

.LBB0_614:
	v_lshlrev_b64 v[126:127], 11, v[200:201]
	v_lshl_add_u64 v[126:127], s[26:27], 0, v[126:127]
	s_andn2_b64 vcc, exec, s[34:35]
	v_lshl_add_u64 v[126:127], v[184:185], 1, v[126:127]
	s_cbranch_vccnz .LBB0_616
	s_nop 1
	v_cvt_pk_bf16_f32 v118, v122, v123
	v_cvt_pk_bf16_f32 v119, v124, v125
	flat_store_dwordx2 v[126:127], v[118:119]

.LBB0_618:
	s_andn2_b64 vcc, exec, s[34:35]
	s_cbranch_vccnz .LBB0_620
	s_nop 1
	v_cvt_pk_bf16_f32 v114, v118, v119
	v_cvt_pk_bf16_f32 v115, v120, v121
	flat_store_dwordx2 v[126:127], v[114:115] offset:32

.LBB0_622:
	s_andn2_b64 vcc, exec, s[34:35]
	s_cbranch_vccnz .LBB0_624
	s_nop 1
	v_cvt_pk_bf16_f32 v110, v114, v115
	v_cvt_pk_bf16_f32 v111, v116, v117
	flat_store_dwordx2 v[126:127], v[110:111] offset:256

.LBB0_626:
	s_andn2_b64 vcc, exec, s[34:35]
	s_cbranch_vccnz .LBB0_628
	v_cvt_pk_bf16_f32 v34, v110, v111
	v_cvt_pk_bf16_f32 v35, v112, v113
	flat_store_dwordx2 v[126:127], v[34:35] offset:288

.LBB0_630:
	v_lshlrev_b64 v[110:111], 11, v[202:203]
	v_lshl_add_u64 v[110:111], s[26:27], 0, v[110:111]
	s_andn2_b64 vcc, exec, s[34:35]
	v_lshl_add_u64 v[110:111], v[184:185], 1, v[110:111]
	s_cbranch_vccnz .LBB0_632
	s_nop 1
	v_cvt_pk_bf16_f32 v102, v106, v107
	v_cvt_pk_bf16_f32 v103, v108, v109
	flat_store_dwordx2 v[110:111], v[102:103]

.LBB0_634:
	s_andn2_b64 vcc, exec, s[34:35]
	s_cbranch_vccnz .LBB0_636
	s_nop 1
	v_cvt_pk_bf16_f32 v98, v102, v103
	v_cvt_pk_bf16_f32 v99, v104, v105
	flat_store_dwordx2 v[110:111], v[98:99] offset:32

.LBB0_638:
	s_andn2_b64 vcc, exec, s[34:35]
	s_cbranch_vccnz .LBB0_640
	s_nop 1
	v_cvt_pk_bf16_f32 v94, v98, v99
	v_cvt_pk_bf16_f32 v95, v100, v101
	flat_store_dwordx2 v[110:111], v[94:95] offset:256

.LBB0_642:
	s_andn2_b64 vcc, exec, s[34:35]
	s_cbranch_vccnz .LBB0_644
	v_cvt_pk_bf16_f32 v34, v94, v95
	v_cvt_pk_bf16_f32 v35, v96, v97
	flat_store_dwordx2 v[110:111], v[34:35] offset:288

.LBB0_646:
	v_lshlrev_b64 v[94:95], 11, v[194:195]
	v_lshl_add_u64 v[94:95], s[26:27], 0, v[94:95]
	s_andn2_b64 vcc, exec, s[34:35]
	v_lshl_add_u64 v[94:95], v[184:185], 1, v[94:95]
	s_cbranch_vccnz .LBB0_648
	s_nop 1
	v_cvt_pk_bf16_f32 v86, v90, v91
	v_cvt_pk_bf16_f32 v87, v92, v93
	flat_store_dwordx2 v[94:95], v[86:87]

.LBB0_650:
	s_andn2_b64 vcc, exec, s[34:35]
	s_cbranch_vccnz .LBB0_652
	s_nop 1
	v_cvt_pk_bf16_f32 v82, v86, v87
	v_cvt_pk_bf16_f32 v83, v88, v89
	flat_store_dwordx2 v[94:95], v[82:83] offset:32

.LBB0_654:
	s_andn2_b64 vcc, exec, s[34:35]
	s_cbranch_vccnz .LBB0_656
	s_nop 1
	v_cvt_pk_bf16_f32 v78, v82, v83
	v_cvt_pk_bf16_f32 v79, v84, v85
	flat_store_dwordx2 v[94:95], v[78:79] offset:256

.LBB0_658:
	s_andn2_b64 vcc, exec, s[34:35]
	s_cbranch_vccnz .LBB0_660
	v_cvt_pk_bf16_f32 v34, v78, v79
	v_cvt_pk_bf16_f32 v35, v80, v81
	flat_store_dwordx2 v[94:95], v[34:35] offset:288

.LBB0_662:
	v_lshlrev_b64 v[78:79], 11, v[192:193]
	v_lshl_add_u64 v[78:79], s[26:27], 0, v[78:79]
	s_andn2_b64 vcc, exec, s[34:35]
	v_lshl_add_u64 v[78:79], v[184:185], 1, v[78:79]
	s_cbranch_vccnz .LBB0_664
	s_nop 1
	v_cvt_pk_bf16_f32 v70, v74, v75
	v_cvt_pk_bf16_f32 v71, v76, v77
	flat_store_dwordx2 v[78:79], v[70:71]

.LBB0_666:
	s_andn2_b64 vcc, exec, s[34:35]
	s_cbranch_vccnz .LBB0_668
	s_nop 1
	v_cvt_pk_bf16_f32 v66, v70, v71
	v_cvt_pk_bf16_f32 v67, v72, v73
	flat_store_dwordx2 v[78:79], v[66:67] offset:32

.LBB0_670:
	s_andn2_b64 vcc, exec, s[34:35]
	s_cbranch_vccnz .LBB0_672
	s_nop 1
	v_cvt_pk_bf16_f32 v62, v66, v67
	v_cvt_pk_bf16_f32 v63, v68, v69
	flat_store_dwordx2 v[78:79], v[62:63] offset:256

.LBB0_674:
	s_andn2_b64 vcc, exec, s[34:35]
	s_cbranch_vccnz .LBB0_676
	v_cvt_pk_bf16_f32 v34, v62, v63
	v_cvt_pk_bf16_f32 v35, v64, v65
	flat_store_dwordx2 v[78:79], v[34:35] offset:288

.LBB0_678:
	v_lshlrev_b64 v[62:63], 11, v[186:187]
	v_lshl_add_u64 v[62:63], s[26:27], 0, v[62:63]
	s_andn2_b64 vcc, exec, s[34:35]
	v_lshl_add_u64 v[62:63], v[184:185], 1, v[62:63]
	s_cbranch_vccnz .LBB0_680
	s_nop 1
	v_cvt_pk_bf16_f32 v54, v58, v59
	v_cvt_pk_bf16_f32 v55, v60, v61
	flat_store_dwordx2 v[62:63], v[54:55]

.LBB0_682:
	s_andn2_b64 vcc, exec, s[34:35]
	s_cbranch_vccnz .LBB0_684
	s_nop 1
	v_cvt_pk_bf16_f32 v50, v54, v55
	v_cvt_pk_bf16_f32 v51, v56, v57
	flat_store_dwordx2 v[62:63], v[50:51] offset:32

.LBB0_686:
	s_andn2_b64 vcc, exec, s[34:35]
	s_cbranch_vccnz .LBB0_688
	s_nop 1
	v_cvt_pk_bf16_f32 v42, v50, v51
	v_cvt_pk_bf16_f32 v43, v52, v53
	flat_store_dwordx2 v[62:63], v[42:43] offset:256

.LBB0_690:
	s_andn2_b64 vcc, exec, s[34:35]
	s_cbranch_vccnz .LBB0_692
	v_cvt_pk_bf16_f32 v34, v42, v43
	v_cvt_pk_bf16_f32 v35, v44, v45
	flat_store_dwordx2 v[62:63], v[34:35] offset:288

.LBB0_694:
	v_lshlrev_b64 v[42:43], 11, v[176:177]
	v_lshl_add_u64 v[42:43], s[26:27], 0, v[42:43]
	s_andn2_b64 vcc, exec, s[34:35]
	v_lshl_add_u64 v[42:43], v[184:185], 1, v[42:43]
	s_cbranch_vccnz .LBB0_696
	s_nop 1
	v_cvt_pk_bf16_f32 v28, v38, v39
	v_cvt_pk_bf16_f32 v29, v40, v41
	flat_store_dwordx2 v[42:43], v[28:29]

.LBB0_698:
	s_andn2_b64 vcc, exec, s[34:35]
	s_cbranch_vccnz .LBB0_700
	s_nop 1
	v_cvt_pk_bf16_f32 v24, v28, v29
	v_cvt_pk_bf16_f32 v25, v30, v31
	flat_store_dwordx2 v[42:43], v[24:25] offset:32

.LBB0_702:
	s_andn2_b64 vcc, exec, s[34:35]
	s_cbranch_vccnz .LBB0_704
	s_nop 1
	v_cvt_pk_bf16_f32 v20, v24, v25
	v_cvt_pk_bf16_f32 v21, v26, v27
	flat_store_dwordx2 v[42:43], v[20:21] offset:256

.LBB0_706:
	s_andn2_b64 vcc, exec, s[34:35]
	s_cbranch_vccnz .LBB0_708
	s_nop 1
	v_cvt_pk_bf16_f32 v16, v20, v21
	v_cvt_pk_bf16_f32 v17, v22, v23
	flat_store_dwordx2 v[42:43], v[16:17] offset:288

.LBB0_710:
	v_lshlrev_b64 v[22:23], 11, v[172:173]
	v_lshl_add_u64 v[22:23], s[26:27], 0, v[22:23]
	s_andn2_b64 vcc, exec, s[24:25]
	v_lshl_add_u64 v[22:23], v[184:185], 1, v[22:23]
	s_cbranch_vccnz .LBB0_712
	s_nop 1
	v_cvt_pk_bf16_f32 v12, v16, v17
	v_cvt_pk_bf16_f32 v13, v18, v19
	flat_store_dwordx2 v[22:23], v[12:13]

.LBB0_714:
	s_andn2_b64 vcc, exec, s[24:25]
	s_cbranch_vccnz .LBB0_716
	s_nop 1
	v_cvt_pk_bf16_f32 v8, v12, v13
	v_cvt_pk_bf16_f32 v9, v14, v15
	flat_store_dwordx2 v[22:23], v[8:9] offset:32

.LBB0_718:
	s_andn2_b64 vcc, exec, s[24:25]
	s_cbranch_vccnz .LBB0_720
	s_nop 1
	v_cvt_pk_bf16_f32 v4, v8, v9
	v_cvt_pk_bf16_f32 v5, v10, v11
	flat_store_dwordx2 v[22:23], v[4:5] offset:256

.LBB0_722:
	s_andn2_b64 vcc, exec, s[24:25]
	s_cbranch_vccnz .LBB0_724
	v_cvt_pk_bf16_f32 v4, v4, v5
	v_cvt_pk_bf16_f32 v5, v6, v7
	flat_store_dwordx2 v[22:23], v[4:5] offset:288

.LBB0_908:
	s_cmp_lg_u32 s49, 0
	s_cbranch_scc1 .Lmy_xs2_skip
	v_lshl_add_u64 v[166:167], s[24:25], 0, v[208:209]
	v_lshl_add_u64 v[166:167], v[184:185], 2, v[166:167]
	global_store_dwordx4 v[166:167], v[134:137], off
	global_store_dwordx4 v[166:167], v[130:133], off offset:64
	global_store_dwordx4 v[166:167], v[126:129], off offset:512
	global_store_dwordx4 v[166:167], v[122:125], off offset:576
	v_lshl_add_u64 v[168:169], s[24:25], 0, v[204:205]
	v_lshl_add_u64 v[168:169], v[184:185], 2, v[168:169]
	global_store_dwordx4 v[168:169], v[118:121], off
	global_store_dwordx4 v[168:169], v[114:117], off offset:64
	global_store_dwordx4 v[168:169], v[110:113], off offset:512
	global_store_dwordx4 v[168:169], v[106:109], off offset:576
	v_lshl_add_u64 v[166:167], s[24:25], 0, v[206:207]
	v_lshl_add_u64 v[166:167], v[184:185], 2, v[166:167]
	global_store_dwordx4 v[166:167], v[102:105], off
	global_store_dwordx4 v[166:167], v[98:101], off offset:64
	global_store_dwordx4 v[166:167], v[94:97], off offset:512
	global_store_dwordx4 v[166:167], v[90:93], off offset:576
	v_lshl_add_u64 v[168:169], s[24:25], 0, v[198:199]
	v_lshl_add_u64 v[168:169], v[184:185], 2, v[168:169]
	global_store_dwordx4 v[168:169], v[86:89], off
	global_store_dwordx4 v[168:169], v[82:85], off offset:64
	global_store_dwordx4 v[168:169], v[78:81], off offset:512
	global_store_dwordx4 v[168:169], v[74:77], off offset:576
	v_lshl_add_u64 v[166:167], s[24:25], 0, v[196:197]
	v_lshl_add_u64 v[166:167], v[184:185], 2, v[166:167]
	global_store_dwordx4 v[166:167], v[70:73], off
	global_store_dwordx4 v[166:167], v[66:69], off offset:64
	global_store_dwordx4 v[166:167], v[62:65], off offset:512
	global_store_dwordx4 v[166:167], v[54:57], off offset:576
	v_lshl_add_u64 v[168:169], s[24:25], 0, v[190:191]
	v_lshl_add_u64 v[168:169], v[184:185], 2, v[168:169]
	global_store_dwordx4 v[168:169], v[50:53], off
	global_store_dwordx4 v[168:169], v[46:49], off offset:64
	global_store_dwordx4 v[168:169], v[42:45], off offset:512
	global_store_dwordx4 v[168:169], v[38:41], off offset:576
	v_lshl_add_u64 v[166:167], s[24:25], 0, v[188:189]
	v_lshl_add_u64 v[166:167], v[184:185], 2, v[166:167]
	global_store_dwordx4 v[166:167], v[28:31], off
	global_store_dwordx4 v[166:167], v[24:27], off offset:64
	global_store_dwordx4 v[166:167], v[20:23], off offset:512
	global_store_dwordx4 v[166:167], v[16:19], off offset:576
	v_lshl_add_u64 v[168:169], s[24:25], 0, v[174:175]
	v_lshl_add_u64 v[168:169], v[184:185], 2, v[168:169]
	global_store_dwordx4 v[168:169], v[12:15], off
	global_store_dwordx4 v[168:169], v[8:11], off offset:64
	global_store_dwordx4 v[168:169], v[4:7], off offset:512
	global_store_dwordx4 v[168:169], v[0:3], off offset:576

.LBB0_1006:
	v_lshlrev_b64 v[62:63], 11, v[186:187]
	v_lshl_add_u64 v[62:63], s[26:27], 0, v[62:63]
	s_andn2_b64 vcc, exec, s[34:35]
	v_lshl_add_u64 v[62:63], v[184:185], 1, v[62:63]
	s_cbranch_vccnz .LBB0_1008
	s_nop 1
	v_cvt_pk_bf16_f32 v50, v54, v55
	v_cvt_pk_bf16_f32 v51, v56, v57
	flat_store_dwordx2 v[62:63], v[50:51]

.LBB0_1010:
	s_andn2_b64 vcc, exec, s[34:35]
	s_cbranch_vccnz .LBB0_1012
	s_nop 1
	v_cvt_pk_bf16_f32 v46, v50, v51
	v_cvt_pk_bf16_f32 v47, v52, v53
	flat_store_dwordx2 v[62:63], v[46:47] offset:32

.LBB0_1014:
	s_andn2_b64 vcc, exec, s[34:35]
	s_cbranch_vccnz .LBB0_1016
	s_nop 1
	v_cvt_pk_bf16_f32 v42, v46, v47
	v_cvt_pk_bf16_f32 v43, v48, v49
	flat_store_dwordx2 v[62:63], v[42:43] offset:256
